# plus: dilated-attention QK^T section issues all four K-fragment LDS reads of a key block up front (two free register quads, counted lgkmcnt) instead of read-wait-MFMA per fragment
# speedup vs baseline: 1.0017x; 1.0002x over previous
; #define LAS __attribute__((address_space(3)))
; __device__ __forceinline__ void attn_phase(const Ctx& X, bf16_t* ACT, float* LSE, bf16_t* Hb, const int g_lo, const int g_hi, const bool fuse) {
;     ...
;                 for (int kb = 0; kb < 9; ++kb) {
;                     const int j0 = 16 * w + 16 * kb; const int r0 = ((((j0 >> 7) ^ par) & 1) << 7) + (j0 & 127);
;                     f32x4 sv = (f32x4){0.f, 0.f, 0.f, 0.f};
; #pragma unroll
;                     for (int ks = 0; ks < 4; ++ks) { const bf16x8 kf = *(const LAS bf16x8*)(X.lds + (r0 + n) * KP + (32 * ks + 8 * q) * 2); sv = __builtin_amdgcn_mfma_f32_16x16x32_bf16(kf, qf[ks], sv, 0, 0, 0); }
;                     const bool blk_ok = hp || (j0 >= 128);
; #pragma unroll
;                     for (int jj = 0; jj < 4; ++jj) { bool valid = blk_ok;
;                         if (kb == 0) valid = valid && (4 * q + jj >= n);
;                         if (kb == 8) valid = valid && (4 * q + jj <= n);
;                         sv[jj] = valid ? sv[jj] : -INFINITY; }
;                     sacc[kb] = sv;
;                 }
.LBB0_331:
	s_add_i32 s5, s89, s2
	s_and_b32 s5, s5, s3
	s_cmp_lg_u32 s5, 0
	s_cselect_b64 s[58:59], -1, 0
	s_xor_b32 s35, s4, s7
	s_and_b32 s5, s35, 0x80
	v_or_b32_e32 v64, s5, v159
	v_mad_u32_u24 v72, v64, s74, v199
	ds_read_b128 v[64:67], v72
	ds_read_b128 v[68:71], v72 offset:64
	ds_read_b128 v[228:231], v72 offset:128
	ds_read_b128 v[232:235], v72 offset:192
	s_or_b64 s[62:63], s[56:57], s[58:59]
	s_and_b64 vcc, s[62:63], s[40:41]
	s_xor_b32 s5, s4, s8
	s_and_b32 s5, s5, 0x80
	s_waitcnt lgkmcnt(3)
	v_mfma_f32_16x16x32_bf16 v[64:67], v[64:67], v[60:63], 0
	s_waitcnt lgkmcnt(2)
	v_mfma_f32_16x16x32_bf16 v[64:67], v[68:71], v[56:59], v[64:67]
	s_waitcnt lgkmcnt(1)
	v_mfma_f32_16x16x32_bf16 v[64:67], v[228:231], v[52:55], v[64:67]
	s_waitcnt lgkmcnt(0)
	v_mfma_f32_16x16x32_bf16 v[68:71], v[232:235], v[48:51], v[64:67]
	s_nop 7
	v_cndmask_b32_e32 v67, v186, v68, vcc
	s_and_b64 vcc, s[62:63], s[42:43]
	v_cndmask_b32_e32 v66, v186, v69, vcc
	s_and_b64 vcc, s[62:63], s[44:45]
	v_or_b32_e32 v68, s5, v192
	v_cndmask_b32_e32 v65, v186, v70, vcc
	s_and_b64 vcc, s[62:63], s[46:47]
	v_mad_u32_u24 v76, v68, s74, v199
	v_cndmask_b32_e32 v64, v186, v71, vcc
	ds_read_b128 v[68:71], v76
	ds_read_b128 v[72:75], v76 offset:64
	ds_read_b128 v[228:231], v76 offset:128
	ds_read_b128 v[232:235], v76 offset:192
	s_waitcnt lgkmcnt(3)
	v_mfma_f32_16x16x32_bf16 v[68:71], v[68:71], v[60:63], 0
	s_xor_b32 s5, s4, s9
	s_and_b32 s5, s5, 0x80
	s_or_b64 vcc, s[20:21], s[58:59]
	s_waitcnt lgkmcnt(2)
	v_mfma_f32_16x16x32_bf16 v[68:71], v[72:75], v[56:59], v[68:71]
	s_waitcnt lgkmcnt(1)
	v_mfma_f32_16x16x32_bf16 v[68:71], v[228:231], v[52:55], v[68:71]
	s_waitcnt lgkmcnt(0)
	v_mfma_f32_16x16x32_bf16 v[72:75], v[232:235], v[48:51], v[68:71]
	s_nop 4
	v_or_b32_e32 v71, s5, v193
	v_mad_u32_u24 v71, v71, s74, v199
	ds_read_b128 v[78:81], v71 offset:64
	v_cndmask_b32_e32 v69, v186, v74, vcc
	v_cndmask_b32_e32 v68, v186, v75, vcc
	ds_read_b128 v[74:77], v71
	ds_read_b128 v[228:231], v71 offset:128
	ds_read_b128 v[232:235], v71 offset:192
	s_waitcnt lgkmcnt(2)
	v_mfma_f32_16x16x32_bf16 v[74:77], v[74:77], v[60:63], 0
	s_xor_b32 s5, s4, s10
	v_cndmask_b32_e32 v72, v186, v72, vcc
	v_cndmask_b32_e32 v70, v186, v73, vcc
	v_mfma_f32_16x16x32_bf16 v[74:77], v[78:81], v[56:59], v[74:77]
	s_or_b64 vcc, s[78:79], s[58:59]
	s_and_b32 s5, s5, 0x80
	s_waitcnt lgkmcnt(1)
	v_mfma_f32_16x16x32_bf16 v[74:77], v[228:231], v[52:55], v[74:77]
	s_waitcnt lgkmcnt(0)
	v_mfma_f32_16x16x32_bf16 v[76:79], v[232:235], v[48:51], v[74:77]
	s_nop 7
	v_cndmask_b32_e32 v75, v186, v76, vcc
	v_or_b32_e32 v76, s5, v194
	v_mad_u32_u24 v84, v76, s74, v199
	v_cndmask_b32_e32 v74, v186, v77, vcc
	v_cndmask_b32_e32 v73, v186, v78, vcc
	v_cndmask_b32_e32 v71, v186, v79, vcc
	ds_read_b128 v[76:79], v84
	ds_read_b128 v[80:83], v84 offset:64
	ds_read_b128 v[228:231], v84 offset:128
	ds_read_b128 v[232:235], v84 offset:192
	s_waitcnt lgkmcnt(3)
	v_mfma_f32_16x16x32_bf16 v[76:79], v[76:79], v[60:63], 0
	s_xor_b32 s5, s4, s11
	s_and_b32 s5, s5, 0x80
	s_or_b64 vcc, s[84:85], s[58:59]
	s_waitcnt lgkmcnt(2)
	v_mfma_f32_16x16x32_bf16 v[76:79], v[80:83], v[56:59], v[76:79]
	s_waitcnt lgkmcnt(1)
	v_mfma_f32_16x16x32_bf16 v[76:79], v[228:231], v[52:55], v[76:79]
	s_waitcnt lgkmcnt(0)
	v_mfma_f32_16x16x32_bf16 v[80:83], v[232:235], v[48:51], v[76:79]
	s_nop 4
	v_or_b32_e32 v76, s5, v201
	v_mad_u32_u24 v76, v76, s74, v199
	ds_read_b128 v[86:89], v76 offset:64
	v_cndmask_b32_e32 v78, v186, v82, vcc
	v_cndmask_b32_e32 v77, v186, v83, vcc
	ds_read_b128 v[82:85], v76
	ds_read_b128 v[228:231], v76 offset:128
	ds_read_b128 v[232:235], v76 offset:192
	s_waitcnt lgkmcnt(2)
	v_mfma_f32_16x16x32_bf16 v[82:85], v[82:85], v[60:63], 0
	s_xor_b32 s5, s4, s12
	s_and_b32 s5, s5, 0x80
	v_cndmask_b32_e32 v80, v186, v80, vcc
	v_mfma_f32_16x16x32_bf16 v[82:85], v[86:89], v[56:59], v[82:85]
	v_cndmask_b32_e32 v79, v186, v81, vcc
	s_or_b64 vcc, s[18:19], s[58:59]
	s_waitcnt lgkmcnt(1)
	v_mfma_f32_16x16x32_bf16 v[82:85], v[228:231], v[52:55], v[82:85]
	v_or_b32_e32 v76, s5, v202
	v_mad_u32_u24 v76, v76, s74, v199
	s_waitcnt lgkmcnt(0)
	v_mfma_f32_16x16x32_bf16 v[84:87], v[232:235], v[48:51], v[82:85]
	ds_read_b128 v[90:93], v76 offset:64
	s_xor_b32 s5, s4, s13
	s_and_b32 s5, s5, 0x80
	s_nop 4
	v_cndmask_b32_e32 v82, v186, v86, vcc
	v_cndmask_b32_e32 v81, v186, v87, vcc
	ds_read_b128 v[86:89], v76
	ds_read_b128 v[228:231], v76 offset:128
	ds_read_b128 v[232:235], v76 offset:192
	s_waitcnt lgkmcnt(2)
	v_mfma_f32_16x16x32_bf16 v[86:89], v[86:89], v[60:63], 0
	v_cndmask_b32_e32 v84, v186, v84, vcc
	v_cndmask_b32_e32 v83, v186, v85, vcc
	s_or_b64 vcc, s[24:25], s[58:59]
	v_mfma_f32_16x16x32_bf16 v[86:89], v[90:93], v[56:59], v[86:89]
	s_waitcnt lgkmcnt(1)
	v_mfma_f32_16x16x32_bf16 v[86:89], v[228:231], v[52:55], v[86:89]
	v_or_b32_e32 v76, s5, v203
	v_mad_u32_u24 v76, v76, s74, v199
	s_waitcnt lgkmcnt(0)
	v_mfma_f32_16x16x32_bf16 v[88:91], v[232:235], v[48:51], v[86:89]
	ds_read_b128 v[94:97], v76 offset:64
	s_xor_b32 s5, s4, s14
	s_and_b32 s5, s5, 0x80
	s_nop 4
	v_cndmask_b32_e32 v86, v186, v90, vcc
	v_cndmask_b32_e32 v85, v186, v91, vcc
	ds_read_b128 v[90:93], v76
	ds_read_b128 v[228:231], v76 offset:128
	ds_read_b128 v[232:235], v76 offset:192
	s_waitcnt lgkmcnt(2)
	v_mfma_f32_16x16x32_bf16 v[90:93], v[90:93], v[60:63], 0
	v_cndmask_b32_e32 v88, v186, v88, vcc
	v_cndmask_b32_e32 v87, v186, v89, vcc
	s_or_b64 vcc, s[94:95], s[58:59]
	v_mfma_f32_16x16x32_bf16 v[90:93], v[94:97], v[56:59], v[90:93]
	s_waitcnt lgkmcnt(1)
	v_mfma_f32_16x16x32_bf16 v[90:93], v[228:231], v[52:55], v[90:93]
	v_or_b32_e32 v76, s5, v204
	v_mad_u32_u24 v76, v76, s74, v199
	s_waitcnt lgkmcnt(0)
; #define LAS __attribute__((address_space(3)))
; __device__ __forceinline__ void attn_phase(const Ctx& X, bf16_t* ACT, float* LSE, bf16_t* Hb, const int g_lo, const int g_hi, const bool fuse) {
;     ...
;                 for (int kb = 0; kb < 9; ++kb) {
;                     const int j0 = 16 * w + 16 * kb; const int r0 = ((((j0 >> 7) ^ par) & 1) << 7) + (j0 & 127);
;                     f32x4 sv = (f32x4){0.f, 0.f, 0.f, 0.f};
; #pragma unroll
;                     for (int ks = 0; ks < 4; ++ks) { const bf16x8 kf = *(const LAS bf16x8*)(X.lds + (r0 + n) * KP + (32 * ks + 8 * q) * 2); sv = __builtin_amdgcn_mfma_f32_16x16x32_bf16(kf, qf[ks], sv, 0, 0, 0); }
;                     const bool blk_ok = hp || (j0 >= 128);
; #pragma unroll
;                     for (int jj = 0; jj < 4; ++jj) { bool valid = blk_ok;
;                         if (kb == 0) valid = valid && (4 * q + jj >= n);
;                         if (kb == 8) valid = valid && (4 * q + jj <= n);
;                         sv[jj] = valid ? sv[jj] : -INFINITY; }
;                     sacc[kb] = sv;
;                 }
;                 float mx = -INFINITY;
; #pragma unroll
;                 for (int kb = 0; kb < 9; ++kb)
; #pragma unroll
;                     for (int jj = 0; jj < 4; ++jj) mx = fmaxf(mx, sacc[kb][jj]);
;                 mx = fmaxf(mx, __shfl_xor(mx, 16)); mx = fmaxf(mx, __shfl_xor(mx, 32));
;                 const float sc2 = 0.08838834764831845f * 1.4426950408889634f; float l = 0.f;
; #pragma unroll
;                 for (int kb = 0; kb < 9; ++kb)
; #pragma unroll
;                     for (int jj = 0; jj < 4; ++jj) { const float p = __builtin_amdgcn_exp2f((sacc[kb][jj] - mx) * sc2); sacc[kb][jj] = p; l += p; }
;                 sacc[9] = (f32x4){0.f, 0.f, 0.f, 0.f};
;                 l += __shfl_xor(l, 16); l += __shfl_xor(l, 32);
	v_mfma_f32_16x16x32_bf16 v[90:93], v[232:235], v[48:51], v[90:93]
	ds_read_b128 v[94:97], v76 offset:64
	s_mov_b32 s5, 0xff800000
	s_nop 5
	v_cndmask_b32_e32 v98, v186, v90, vcc
	v_cndmask_b32_e32 v99, v186, v91, vcc
	v_cndmask_b32_e32 v100, v186, v92, vcc
	v_cndmask_b32_e32 v101, v186, v93, vcc
	ds_read_b128 v[90:93], v76
	ds_read_b128 v[228:231], v76 offset:128
	ds_read_b128 v[232:235], v76 offset:192
	s_waitcnt lgkmcnt(2)
	v_mfma_f32_16x16x32_bf16 v[90:93], v[90:93], v[60:63], 0
	s_or_b64 vcc, s[90:91], s[58:59]
	s_or_b64 s[58:59], s[30:31], s[58:59]
	v_mfma_f32_16x16x32_bf16 v[90:93], v[94:97], v[56:59], v[90:93]
	s_waitcnt lgkmcnt(1)
	v_mfma_f32_16x16x32_bf16 v[90:93], v[228:231], v[52:55], v[90:93]
	v_bitop3_b32 v76, s35, v187, v159 bitop3:0x26
	v_mad_u32_u24 v76, v76, s74, v199
	s_waitcnt lgkmcnt(0)
	v_mfma_f32_16x16x32_bf16 v[90:93], v[232:235], v[48:51], v[90:93]
	s_xor_b32 s35, s4, s77
	s_and_b32 s35, s35, 0x80
	s_nop 5
	v_cndmask_b32_e32 v96, v186, v90, vcc
	v_cndmask_b32_e32 v97, v186, v91, vcc
	v_cndmask_b32_e32 v102, v186, v92, vcc
	v_cndmask_b32_e32 v103, v186, v93, vcc
	ds_read_b128 v[90:93], v76
	s_waitcnt lgkmcnt(0)
	v_mfma_f32_16x16x32_bf16 v[60:63], v[90:93], v[60:63], 0
	ds_read_b128 v[90:93], v76 offset:64
	s_and_b64 vcc, s[58:59], s[48:49]
	s_waitcnt lgkmcnt(0)
	v_mfma_f32_16x16x32_bf16 v[56:59], v[90:93], v[56:59], v[60:63]
	s_nop 3
	ds_read_b128 v[60:63], v76 offset:128
	s_waitcnt lgkmcnt(0)
	v_mfma_f32_16x16x32_bf16 v[52:55], v[60:63], v[52:55], v[56:59]
	s_nop 2
	ds_read_b128 v[56:59], v76 offset:192
	s_waitcnt lgkmcnt(0)
	v_mfma_f32_16x16x32_bf16 v[48:51], v[56:59], v[48:51], v[52:55]
	s_nop 2
	v_max3_f32 v52, v67, s5, v66
	v_max3_f32 v52, v52, v65, v64
	v_max3_f32 v52, v52, v72, v70
	v_max3_f32 v52, v52, v69, v68
	v_max3_f32 v52, v52, v75, v74
	v_max3_f32 v52, v52, v73, v71
	v_max3_f32 v52, v52, v80, v79
	v_max3_f32 v52, v52, v78, v77
	v_max3_f32 v52, v52, v84, v83
	v_max3_f32 v52, v52, v82, v81
	v_max3_f32 v52, v52, v88, v87
	v_max3_f32 v52, v52, v86, v85
	v_cndmask_b32_e32 v48, v186, v48, vcc
	s_and_b64 vcc, s[58:59], s[50:51]
	v_max3_f32 v52, v52, v98, v99
	v_cndmask_b32_e32 v49, v186, v49, vcc
	s_and_b64 vcc, s[58:59], s[52:53]
	v_max3_f32 v52, v52, v100, v101
	v_and_b32_e32 v54, 64, v183
	v_cndmask_b32_e32 v50, v186, v50, vcc
	s_and_b64 vcc, s[58:59], s[54:55]
	v_max3_f32 v52, v52, v96, v97
	v_xor_b32_e32 v53, 16, v183
	v_add_u32_e32 v54, 64, v54
	v_cndmask_b32_e32 v51, v186, v51, vcc
	v_max3_f32 v52, v52, v102, v103
	v_cmp_lt_i32_e32 vcc, v53, v54
	v_max3_f32 v52, v52, v48, v49
	v_max3_f32 v52, v52, v50, v51
	v_cndmask_b32_e32 v53, v183, v53, vcc
	v_lshlrev_b32_e32 v104, 2, v53
	ds_bpermute_b32 v53, v104, v52
	s_xor_b32 s5, s4, s15
	s_and_b32 s5, s5, 0x80
	s_waitcnt lgkmcnt(0)
	v_max_f32_e32 v53, v53, v53
	v_max_f32_e32 v52, v52, v53
	v_xor_b32_e32 v53, 32, v183
	v_cmp_lt_i32_e32 vcc, v53, v54
	s_nop 1
	v_cndmask_b32_e32 v53, v183, v53, vcc
	v_lshlrev_b32_e32 v105, 2, v53
	ds_bpermute_b32 v53, v105, v52
	s_waitcnt lgkmcnt(0)
	v_max_f32_e32 v53, v53, v53
	v_max_f32_e32 v76, v52, v53
	v_sub_f32_e32 v53, v66, v76
	v_mul_f32_e32 v53, 0x3e0293ee, v53
	v_exp_f32_e32 v90, v53
	v_sub_f32_e32 v53, v65, v76
	v_mul_f32_e32 v53, 0x3e0293ee, v53
	v_exp_f32_e32 v91, v53
	v_sub_f32_e32 v53, v64, v76
	v_mul_f32_e32 v53, 0x3e0293ee, v53
	v_exp_f32_e32 v92, v53
	v_sub_f32_e32 v53, v72, v76
	v_mul_f32_e32 v53, 0x3e0293ee, v53
	v_exp_f32_e32 v93, v53
	v_sub_f32_e32 v53, v70, v76
	v_mul_f32_e32 v53, 0x3e0293ee, v53
	v_exp_f32_e32 v94, v53
	v_sub_f32_e32 v53, v69, v76
	v_mul_f32_e32 v53, 0x3e0293ee, v53
	v_exp_f32_e32 v95, v53
	v_sub_f32_e32 v53, v68, v76
	v_mul_f32_e32 v53, 0x3e0293ee, v53
	v_exp_f32_e32 v106, v53
	v_sub_f32_e32 v53, v75, v76
	v_mul_f32_e32 v53, 0x3e0293ee, v53
	v_exp_f32_e32 v68, v53
	v_sub_f32_e32 v53, v74, v76
	v_mul_f32_e32 v53, 0x3e0293ee, v53
	v_exp_f32_e32 v69, v53
	v_sub_f32_e32 v53, v73, v76
	v_mul_f32_e32 v53, 0x3e0293ee, v53
	v_exp_f32_e32 v70, v53
	v_sub_f32_e32 v53, v71, v76
	v_sub_f32_e32 v52, v67, v76
	v_mul_f32_e32 v53, 0x3e0293ee, v53
	v_mul_f32_e32 v52, 0x3e0293ee, v52
	v_exp_f32_e32 v71, v53
	v_sub_f32_e32 v53, v80, v76
	v_exp_f32_e32 v89, v52
	v_mul_f32_e32 v53, 0x3e0293ee, v53
	v_exp_f32_e32 v72, v53
	v_sub_f32_e32 v53, v79, v76
	v_mul_f32_e32 v53, 0x3e0293ee, v53
	v_exp_f32_e32 v73, v53
	v_sub_f32_e32 v53, v78, v76
	v_add_f32_e32 v52, 0, v89
	v_mul_f32_e32 v53, 0x3e0293ee, v53
	v_add_f32_e32 v52, v90, v52
	v_exp_f32_e32 v74, v53
	v_sub_f32_e32 v53, v77, v76
	v_add_f32_e32 v52, v91, v52
	v_mul_f32_e32 v53, 0x3e0293ee, v53
	v_add_f32_e32 v52, v92, v52
	v_exp_f32_e32 v75, v53
	v_sub_f32_e32 v53, v84, v76
	v_add_f32_e32 v52, v93, v52
	v_mul_f32_e32 v53, 0x3e0293ee, v53
	v_add_f32_e32 v52, v94, v52
	v_exp_f32_e32 v60, v53
	v_sub_f32_e32 v53, v83, v76
	v_add_f32_e32 v52, v95, v52
	v_mul_f32_e32 v53, 0x3e0293ee, v53
	v_add_f32_e32 v52, v106, v52
	v_exp_f32_e32 v61, v53
	v_sub_f32_e32 v53, v82, v76
	v_add_f32_e32 v52, v68, v52
	v_mul_f32_e32 v53, 0x3e0293ee, v53
	v_add_f32_e32 v52, v69, v52
	v_exp_f32_e32 v62, v53
	v_sub_f32_e32 v53, v81, v76
	v_add_f32_e32 v52, v70, v52
	v_mul_f32_e32 v53, 0x3e0293ee, v53
	v_add_f32_e32 v52, v71, v52
	v_exp_f32_e32 v63, v53
	v_sub_f32_e32 v53, v88, v76
	v_add_f32_e32 v52, v72, v52
	v_mul_f32_e32 v53, 0x3e0293ee, v53
	v_add_f32_e32 v52, v73, v52
	v_exp_f32_e32 v64, v53
	v_sub_f32_e32 v53, v87, v76
	v_add_f32_e32 v52, v74, v52
	v_mul_f32_e32 v53, 0x3e0293ee, v53
	v_add_f32_e32 v52, v75, v52
	v_exp_f32_e32 v65, v53
	v_sub_f32_e32 v53, v86, v76
	v_add_f32_e32 v52, v60, v52
	v_mul_f32_e32 v53, 0x3e0293ee, v53
	v_add_f32_e32 v52, v61, v52
	v_exp_f32_e32 v66, v53
; #define LAS __attribute__((address_space(3)))
; __device__ __forceinline__ unsigned cvt_pk_bf16(float lo, float hi) { unsigned r; asm volatile("v_cvt_pk_bf16_f32 %0, %1, %2" : "=v"(r) : "v"(lo), "v"(hi)); return r; }
; __device__ __forceinline__ void attn_phase(const Ctx& X, bf16_t* ACT, float* LSE, bf16_t* Hb, const int g_lo, const int g_hi, const bool fuse) {
;     ...
;                 const float sc2 = 0.08838834764831845f * 1.4426950408889634f; float l = 0.f;
; #pragma unroll
;                 for (int kb = 0; kb < 9; ++kb)
; #pragma unroll
;                     for (int jj = 0; jj < 4; ++jj) { const float p = __builtin_amdgcn_exp2f((sacc[kb][jj] - mx) * sc2); sacc[kb][jj] = p; l += p; }
;                 sacc[9] = (f32x4){0.f, 0.f, 0.f, 0.f};
;                 l += __shfl_xor(l, 16); l += __shfl_xor(l, 32);
;                 f32x4 oacc[8];
; #pragma unroll
;                 for (int eb = 0; eb < 8; ++eb) oacc[eb] = (f32x4){0.f, 0.f, 0.f, 0.f};
; #pragma unroll
;                 for (int s2 = 0; s2 < 5; ++s2) {
;                     const int ja = 16 * w + 32 * s2, jb = ja + 16; const int jac = ja > 240 ? 240 : ja, jbc = jb > 240 ? 240 : jb;
;                     const int ca = ((((jac >> 7) ^ par) & 1) << 7) + (jac & 127), cbb = ((((jbc >> 7) ^ par) & 1) << 7) + (jbc & 127);
;                     u32x4 pw; pw.x = cvt_pk_bf16(sacc[2 * s2][0], sacc[2 * s2][1]); pw.y = cvt_pk_bf16(sacc[2 * s2][2], sacc[2 * s2][3]);
;                     pw.z = cvt_pk_bf16(sacc[2 * s2 + 1][0], sacc[2 * s2 + 1][1]); pw.w = cvt_pk_bf16(sacc[2 * s2 + 1][2], sacc[2 * s2 + 1][3]);
;                     const bf16x8 pf = __builtin_bit_cast(bf16x8, pw);
; #pragma unroll
;                     for (int eb = 0; eb < 8; ++eb) { const int e = 16 * eb + n;
;                         const u32x2 va = *(const LAS u32x2*)(X.lds + LDS_V + e * VP + (ca + 4 * q) * 2), vb = *(const LAS u32x2*)(X.lds + LDS_V + e * VP + (cbb + 4 * q) * 2);
;                         const u32x4 vv = (u32x4){va.x, va.y, vb.x, vb.y};
;                         oacc[eb] = __builtin_amdgcn_mfma_f32_16x16x32_bf16(__builtin_bit_cast(bf16x8, vv), pf, oacc[eb], 0, 0, 0); }
	v_sub_f32_e32 v53, v85, v76
	v_add_f32_e32 v52, v62, v52
	v_mul_f32_e32 v53, 0x3e0293ee, v53
	v_add_f32_e32 v52, v63, v52
	v_exp_f32_e32 v67, v53
	v_add_f32_e32 v52, v64, v52
	v_add_f32_e32 v52, v65, v52
	v_add_f32_e32 v52, v66, v52
	v_add_f32_e32 v53, v67, v52
	v_sub_f32_e32 v52, v98, v76
	v_mul_f32_e32 v52, 0x3e0293ee, v52
	v_exp_f32_e32 v52, v52
	v_sub_f32_e32 v48, v48, v76
	v_mul_f32_e32 v48, 0x3e0293ee, v48
	v_sub_f32_e32 v49, v49, v76
	v_add_f32_e32 v54, v52, v53
	v_sub_f32_e32 v53, v99, v76
	v_mul_f32_e32 v53, 0x3e0293ee, v53
	v_exp_f32_e32 v53, v53
	v_exp_f32_e32 v48, v48
	v_mul_f32_e32 v49, 0x3e0293ee, v49
	v_sub_f32_e32 v50, v50, v76
	v_add_f32_e32 v55, v53, v54
	v_sub_f32_e32 v54, v100, v76
	v_mul_f32_e32 v54, 0x3e0293ee, v54
	v_exp_f32_e32 v54, v54
	v_exp_f32_e32 v49, v49
	v_mul_f32_e32 v50, 0x3e0293ee, v50
	v_sub_f32_e32 v51, v51, v76
	v_add_f32_e32 v56, v54, v55
	v_sub_f32_e32 v55, v101, v76
	v_mul_f32_e32 v55, 0x3e0293ee, v55
	v_exp_f32_e32 v55, v55
	v_exp_f32_e32 v50, v50
	v_mul_f32_e32 v51, 0x3e0293ee, v51
	v_exp_f32_e32 v51, v51
	v_add_f32_e32 v57, v55, v56
	v_sub_f32_e32 v56, v96, v76
	v_mul_f32_e32 v56, 0x3e0293ee, v56
	v_exp_f32_e32 v56, v56
	v_or_b32_e32 v79, s5, v205
	v_or_b32_e32 v86, s35, v206
	v_lshl_add_u32 v79, v79, 1, v200
	v_add_f32_e32 v58, v56, v57
	v_sub_f32_e32 v57, v97, v76
	v_mul_f32_e32 v57, 0x3e0293ee, v57
	v_exp_f32_e32 v57, v57
	v_lshl_add_u32 v127, v86, 1, v200
	v_cvt_pk_bf16_f32 v80, v89, v90
	v_cvt_pk_bf16_f32 v81, v91, v92
	v_add_f32_e32 v59, v57, v58
	v_sub_f32_e32 v58, v102, v76
	v_mul_f32_e32 v58, 0x3e0293ee, v58
	v_exp_f32_e32 v58, v58
	v_cvt_pk_bf16_f32 v82, v93, v94
	v_cvt_pk_bf16_f32 v83, v95, v106
	ds_read_b64 v[84:85], v79
	ds_read_b64 v[86:87], v127
	v_add_f32_e32 v77, v58, v59
	v_sub_f32_e32 v59, v103, v76
	v_mul_f32_e32 v59, 0x3e0293ee, v59
	v_exp_f32_e32 v59, v59
	s_xor_b32 s5, s4, s70
	s_xor_b32 s35, s4, s71
	s_and_b32 s5, s5, 0x80
	v_add_f32_e32 v77, v59, v77
	v_add_f32_e32 v77, v48, v77
	v_add_f32_e32 v77, v49, v77
	v_add_f32_e32 v77, v50, v77
	v_add_f32_e32 v77, v51, v77
	ds_bpermute_b32 v78, v104, v77
	s_and_b32 s35, s35, 0x80
	ds_read_b64 v[88:89], v79 offset:8448
	ds_read_b64 v[90:91], v127 offset:8448
	ds_read_b64 v[92:93], v79 offset:16896
	ds_read_b64 v[94:95], v127 offset:16896
	ds_read_b64 v[96:97], v79 offset:25344
	ds_read_b64 v[98:99], v127 offset:25344
	s_waitcnt lgkmcnt(6)
	v_add_f32_e32 v77, v77, v78
	ds_bpermute_b32 v78, v105, v77
	ds_read_b64 v[100:101], v79 offset:33792
	ds_read_b64 v[102:103], v127 offset:33792
	ds_read_b64 v[104:105], v79 offset:42240
	ds_read_b64 v[106:107], v127 offset:42240
	ds_read_b64 v[108:109], v79 offset:50688
	ds_read_b64 v[110:111], v127 offset:50688
	ds_read_b64 v[174:175], v79 offset:59136
	ds_read_b64 v[176:177], v127 offset:59136
	v_cvt_pk_bf16_f32 v68, v68, v69
	v_cvt_pk_bf16_f32 v69, v70, v71
	v_cvt_pk_bf16_f32 v70, v72, v73
	v_cvt_pk_bf16_f32 v71, v74, v75
	v_or_b32_e32 v72, s5, v207
	v_or_b32_e32 v74, s35, v208
	v_lshl_add_u32 v79, v72, 1, v200
	v_lshl_add_u32 v127, v74, 1, v200
	ds_read_b64 v[72:73], v79
	ds_read_b64 v[74:75], v127
	v_mfma_f32_16x16x32_bf16 v[84:87], v[84:87], v[80:83], 0
	s_xor_b32 s5, s4, s67
	s_xor_b32 s35, s4, s68
	s_and_b32 s5, s5, 0x80
	s_waitcnt lgkmcnt(0)
	v_mfma_f32_16x16x32_bf16 v[72:75], v[72:75], v[68:71], v[84:87]
	s_nop 2
	ds_read_b64 v[84:85], v79 offset:8448
	ds_read_b64 v[86:87], v127 offset:8448
	s_and_b32 s35, s35, 0x80
	v_add_f32_e32 v77, v77, v78
	v_mfma_f32_16x16x32_bf16 v[88:91], v[88:91], v[80:83], 0
	v_div_scale_f32 v78, s[58:59], v77, v77, 1.0
	s_waitcnt lgkmcnt(0)
	v_mfma_f32_16x16x32_bf16 v[84:87], v[84:87], v[68:71], v[88:91]
	s_nop 4
	ds_read_b64 v[88:89], v79 offset:16896
	ds_read_b64 v[90:91], v127 offset:16896
	v_mfma_f32_16x16x32_bf16 v[92:95], v[92:95], v[80:83], 0
	s_waitcnt lgkmcnt(0)
	v_mfma_f32_16x16x32_bf16 v[88:91], v[88:91], v[68:71], v[92:95]
	s_nop 5
	ds_read_b64 v[92:93], v79 offset:25344
	ds_read_b64 v[94:95], v127 offset:25344
	v_mfma_f32_16x16x32_bf16 v[96:99], v[96:99], v[80:83], 0
	s_waitcnt lgkmcnt(0)
	v_mfma_f32_16x16x32_bf16 v[92:95], v[92:95], v[68:71], v[96:99]
	s_nop 5
	ds_read_b64 v[96:97], v79 offset:33792
	ds_read_b64 v[98:99], v127 offset:33792
	v_mfma_f32_16x16x32_bf16 v[100:103], v[100:103], v[80:83], 0
	s_waitcnt lgkmcnt(0)
	v_mfma_f32_16x16x32_bf16 v[96:99], v[96:99], v[68:71], v[100:103]
	s_nop 5
	ds_read_b64 v[100:101], v79 offset:42240
	ds_read_b64 v[102:103], v127 offset:42240
	v_mfma_f32_16x16x32_bf16 v[104:107], v[104:107], v[80:83], 0
	s_waitcnt lgkmcnt(0)
	v_mfma_f32_16x16x32_bf16 v[100:103], v[100:103], v[68:71], v[104:107]
	s_nop 5
	ds_read_b64 v[104:105], v79 offset:50688
	ds_read_b64 v[106:107], v127 offset:50688
	v_mfma_f32_16x16x32_bf16 v[108:111], v[108:111], v[80:83], 0
	s_waitcnt lgkmcnt(0)
	v_mfma_f32_16x16x32_bf16 v[104:107], v[104:107], v[68:71], v[108:111]
	s_nop 5
	ds_read_b64 v[108:109], v79 offset:59136
	ds_read_b64 v[110:111], v127 offset:59136
	v_cvt_pk_bf16_f32 v60, v60, v61
	v_cvt_pk_bf16_f32 v61, v62, v63
	v_mfma_f32_16x16x32_bf16 v[80:83], v[174:177], v[80:83], 0
	v_cvt_pk_bf16_f32 v62, v64, v65
	v_cvt_pk_bf16_f32 v63, v66, v67
	v_or_b32_e32 v64, s5, v209
	v_or_b32_e32 v66, s35, v210
	s_waitcnt lgkmcnt(0)
	v_mfma_f32_16x16x32_bf16 v[68:71], v[108:111], v[68:71], v[80:83]
	v_lshl_add_u32 v79, v64, 1, v200
	v_lshl_add_u32 v108, v66, 1, v200
	ds_read_b64 v[64:65], v79
	ds_read_b64 v[66:67], v108
	s_waitcnt lgkmcnt(0)
	v_mfma_f32_16x16x32_bf16 v[64:67], v[64:67], v[60:63], v[72:75]
	s_nop 2
	ds_read_b64 v[72:73], v79 offset:8448
	ds_read_b64 v[74:75], v108 offset:8448
	ds_read_b64 v[80:81], v79 offset:16896
	ds_read_b64 v[82:83], v108 offset:16896
	s_xor_b32 s5, s4, s33
	s_waitcnt lgkmcnt(2)
; #define LAS __attribute__((address_space(3)))
; __device__ __forceinline__ unsigned cvt_pk_bf16(float lo, float hi) { unsigned r; asm volatile("v_cvt_pk_bf16_f32 %0, %1, %2" : "=v"(r) : "v"(lo), "v"(hi)); return r; }
; __device__ __forceinline__ void attn_phase(const Ctx& X, bf16_t* ACT, float* LSE, bf16_t* Hb, const int g_lo, const int g_hi, const bool fuse) {
;     ...
;                 for (int s2 = 0; s2 < 5; ++s2) {
;                     const int ja = 16 * w + 32 * s2, jb = ja + 16; const int jac = ja > 240 ? 240 : ja, jbc = jb > 240 ? 240 : jb;
;                     const int ca = ((((jac >> 7) ^ par) & 1) << 7) + (jac & 127), cbb = ((((jbc >> 7) ^ par) & 1) << 7) + (jbc & 127);
;                     u32x4 pw; pw.x = cvt_pk_bf16(sacc[2 * s2][0], sacc[2 * s2][1]); pw.y = cvt_pk_bf16(sacc[2 * s2][2], sacc[2 * s2][3]);
;                     pw.z = cvt_pk_bf16(sacc[2 * s2 + 1][0], sacc[2 * s2 + 1][1]); pw.w = cvt_pk_bf16(sacc[2 * s2 + 1][2], sacc[2 * s2 + 1][3]);
;                     const bf16x8 pf = __builtin_bit_cast(bf16x8, pw);
; #pragma unroll
;                     for (int eb = 0; eb < 8; ++eb) { const int e = 16 * eb + n;
;                         const u32x2 va = *(const LAS u32x2*)(X.lds + LDS_V + e * VP + (ca + 4 * q) * 2), vb = *(const LAS u32x2*)(X.lds + LDS_V + e * VP + (cbb + 4 * q) * 2);
;                         const u32x4 vv = (u32x4){va.x, va.y, vb.x, vb.y};
;                         oacc[eb] = __builtin_amdgcn_mfma_f32_16x16x32_bf16(__builtin_bit_cast(bf16x8, vv), pf, oacc[eb], 0, 0, 0); }
;                 }
;                 const float il = 1.0f / l; const float lse_own = mx * 0.08838834764831845f + __logf(l);
	v_mfma_f32_16x16x32_bf16 v[72:75], v[72:75], v[60:63], v[84:87]
	s_nop 2
	ds_read_b64 v[84:85], v79 offset:25344
	ds_read_b64 v[86:87], v108 offset:25344
	s_xor_b32 s35, s4, s65
	s_and_b32 s5, s5, 0x80
	s_waitcnt lgkmcnt(2)
	v_mfma_f32_16x16x32_bf16 v[80:83], v[80:83], v[60:63], v[88:91]
	s_nop 2
	ds_read_b64 v[88:89], v79 offset:33792
	ds_read_b64 v[90:91], v108 offset:33792
	s_and_b32 s35, s35, 0x80
	s_waitcnt lgkmcnt(2)
	v_mfma_f32_16x16x32_bf16 v[84:87], v[84:87], v[60:63], v[92:95]
	s_nop 2
	ds_read_b64 v[92:93], v79 offset:42240
	ds_read_b64 v[94:95], v108 offset:42240
	s_waitcnt lgkmcnt(2)
	v_mfma_f32_16x16x32_bf16 v[88:91], v[88:91], v[60:63], v[96:99]
	s_nop 2
	ds_read_b64 v[96:97], v79 offset:50688
	ds_read_b64 v[98:99], v108 offset:50688
	s_waitcnt lgkmcnt(2)
	v_mfma_f32_16x16x32_bf16 v[92:95], v[92:95], v[60:63], v[100:103]
	s_nop 2
	ds_read_b64 v[100:101], v79 offset:59136
	ds_read_b64 v[102:103], v108 offset:59136
	v_cvt_pk_bf16_f32 v52, v52, v53
	v_cvt_pk_bf16_f32 v53, v54, v55
	v_cvt_pk_bf16_f32 v54, v56, v57
	v_cvt_pk_bf16_f32 v55, v58, v59
	v_or_b32_e32 v56, s5, v211
	v_or_b32_e32 v58, s35, v212
	s_waitcnt lgkmcnt(2)
	v_mfma_f32_16x16x32_bf16 v[96:99], v[96:99], v[60:63], v[104:107]
	v_lshl_add_u32 v79, v56, 1, v200
	ds_read_b64 v[56:57], v79
	s_xor_b32 s5, s4, s66
	s_waitcnt lgkmcnt(1)
	v_mfma_f32_16x16x32_bf16 v[60:63], v[100:103], v[60:63], v[68:71]
	v_lshl_add_u32 v100, v58, 1, v200
	ds_read_b64 v[58:59], v100
	s_xor_b32 s35, s4, s69
	s_waitcnt lgkmcnt(0)
	v_mfma_f32_16x16x32_bf16 v[56:59], v[56:59], v[52:55], v[64:67]
	s_nop 2
	ds_read_b64 v[64:65], v79 offset:8448
	ds_read_b64 v[66:67], v100 offset:8448
	ds_read_b64 v[68:69], v79 offset:16896
	ds_read_b64 v[70:71], v100 offset:16896
	s_and_b32 s5, s5, 0x80
	s_waitcnt lgkmcnt(2)
	v_mfma_f32_16x16x32_bf16 v[64:67], v[64:67], v[52:55], v[72:75]
	s_nop 2
	ds_read_b64 v[72:73], v79 offset:25344
	ds_read_b64 v[74:75], v100 offset:25344
	s_and_b32 s35, s35, 0x80
	s_waitcnt lgkmcnt(2)
	v_mfma_f32_16x16x32_bf16 v[68:71], v[68:71], v[52:55], v[80:83]
	s_waitcnt lgkmcnt(0)
	v_mfma_f32_16x16x32_bf16 v[80:83], v[72:75], v[52:55], v[84:87]
	ds_read_b64 v[72:73], v79 offset:33792
	ds_read_b64 v[74:75], v100 offset:33792
	s_waitcnt lgkmcnt(0)
	v_mfma_f32_16x16x32_bf16 v[84:87], v[72:75], v[52:55], v[88:91]
	ds_read_b64 v[72:73], v79 offset:42240
	ds_read_b64 v[74:75], v100 offset:42240
	s_waitcnt lgkmcnt(0)
	v_mfma_f32_16x16x32_bf16 v[88:91], v[72:75], v[52:55], v[92:95]
	ds_read_b64 v[72:73], v79 offset:50688
	ds_read_b64 v[74:75], v100 offset:50688
	s_waitcnt lgkmcnt(0)
	v_mfma_f32_16x16x32_bf16 v[92:95], v[72:75], v[52:55], v[96:99]
	ds_read_b64 v[72:73], v79 offset:59136
	ds_read_b64 v[74:75], v100 offset:59136
	v_cvt_pk_bf16_f32 v48, v48, v49
	v_cvt_pk_bf16_f32 v49, v50, v51
	s_waitcnt lgkmcnt(0)
	v_mfma_f32_16x16x32_bf16 v[96:99], v[72:75], v[52:55], v[60:63]
	v_or_b32_e32 v52, s5, v213
	v_or_b32_e32 v54, s35, v214
	v_lshl_add_u32 v79, v52, 1, v200
	v_lshl_add_u32 v104, v54, 1, v200
	v_cvt_pk_bf16_f32 v50, v145, v145
	v_cvt_pk_bf16_f32 v51, v145, v145
	ds_read_b64 v[52:53], v79
	ds_read_b64 v[54:55], v104
	s_waitcnt lgkmcnt(0)
	v_mfma_f32_16x16x32_bf16 v[100:103], v[52:55], v[48:51], v[56:59]
	ds_read_b64 v[52:53], v79 offset:8448
	ds_read_b64 v[54:55], v104 offset:8448
	s_mov_b32 s5, 0x3f317217
	s_waitcnt lgkmcnt(0)
	v_mfma_f32_16x16x32_bf16 v[72:75], v[52:55], v[48:51], v[64:67]
	ds_read_b64 v[52:53], v79 offset:16896
	ds_read_b64 v[54:55], v104 offset:16896
	s_waitcnt lgkmcnt(0)
	v_mfma_f32_16x16x32_bf16 v[68:71], v[52:55], v[48:51], v[68:71]
	ds_read_b64 v[52:53], v79 offset:25344
	ds_read_b64 v[54:55], v104 offset:25344
	s_waitcnt lgkmcnt(0)
	v_mfma_f32_16x16x32_bf16 v[64:67], v[52:55], v[48:51], v[80:83]
	ds_read_b64 v[52:53], v79 offset:33792
	ds_read_b64 v[54:55], v104 offset:33792
	s_waitcnt lgkmcnt(0)
	v_mfma_f32_16x16x32_bf16 v[60:63], v[52:55], v[48:51], v[84:87]
	ds_read_b64 v[52:53], v79 offset:42240
	ds_read_b64 v[54:55], v104 offset:42240
	s_waitcnt lgkmcnt(0)
	v_mfma_f32_16x16x32_bf16 v[56:59], v[52:55], v[48:51], v[88:91]
	ds_read_b64 v[52:53], v79 offset:50688
	ds_read_b64 v[54:55], v104 offset:50688
	ds_read_b64 v[80:81], v79 offset:59136
	ds_read_b64 v[82:83], v104 offset:59136
	v_rcp_f32_e32 v79, v78
	s_waitcnt lgkmcnt(2)
	v_mfma_f32_16x16x32_bf16 v[52:55], v[52:55], v[48:51], v[92:95]
	s_waitcnt lgkmcnt(0)
	v_mfma_f32_16x16x32_bf16 v[48:51], v[80:83], v[48:51], v[96:99]
	v_fma_f32 v80, -v78, v79, 1.0
	v_fmac_f32_e32 v79, v80, v79
	v_div_scale_f32 v80, vcc, 1.0, v77, 1.0
	v_mul_f32_e32 v81, v80, v79
	v_fma_f32 v82, -v78, v81, v80
	v_fmac_f32_e32 v81, v82, v79
	v_fma_f32 v78, -v78, v81, v80
	v_div_fmas_f32 v78, v78, v79, v81
	v_cmp_gt_f32_e32 vcc, s73, v77
	v_div_fixup_f32 v176, v78, v77, 1.0
	s_nop 0
	v_cndmask_b32_e64 v78, 0, 32, vcc
	v_ldexp_f32 v77, v77, v78
	v_log_f32_e32 v77, v77
	s_nop 0
	v_mul_f32_e32 v78, 0x3f317217, v77
	v_fma_f32 v78, v77, s5, -v78
	v_fmac_f32_e32 v78, 0x3377d1cf, v77
	s_mov_b32 s5, 0x7f800000
	v_fmac_f32_e32 v78, 0x3f317217, v77
	v_cmp_lt_f32_e64 s[58:59], |v77|, s5
	s_nop 1
	v_cndmask_b32_e64 v77, v77, v78, s[58:59]
	v_cndmask_b32_e32 v78, 0, v188, vcc
	v_sub_f32_e32 v127, v77, v78
	v_fmac_f32_e32 v127, 0x3db504f3, v76
	s_mov_b64 s[58:59], -1
	s_andn2_b64 vcc, exec, s[36:37]
	s_cbranch_vccnz .LBB0_335
; __device__ __forceinline__ unsigned cvt_pk_bf16(float lo, float hi) { unsigned r; asm volatile("v_cvt_pk_bf16_f32 %0, %1, %2" : "=v"(r) : "v"(lo), "v"(hi)); return r; }
; __device__ __forceinline__ void attn_phase(const Ctx& X, bf16_t* ACT, float* LSE, bf16_t* Hb, const int g_lo, const int g_hi, const bool fuse) {
;     ...
;                 const float il = 1.0f / l; const float lse_own = mx * 0.08838834764831845f + __logf(l);
;                 const int ecol = (q & 1) ? 16 + 4 * (q - 1) : 4 * q;
;                 if (!fuse) {
; #pragma unroll
;                     for (int eb = 0; eb < 8; eb += 2) {
;                         const unsigned a0 = cvt_pk_bf16(oacc[eb][0] * il, oacc[eb][1] * il), a1 = cvt_pk_bf16(oacc[eb][2] * il, oacc[eb][3] * il);
;                         const unsigned b0 = cvt_pk_bf16(oacc[eb + 1][0] * il, oacc[eb + 1][1] * il), b1 = cvt_pk_bf16(oacc[eb + 1][2] * il, oacc[eb + 1][3] * il);
;                         const auto s0 = __builtin_amdgcn_permlane16_swap(a0, b0, false, false), s1 = __builtin_amdgcn_permlane16_swap(a1, b1, false, false);
;                         *(u32x4*)(qrow + 16 * eb + ecol) = (u32x4){s0[0], s1[0], s0[1], s1[1]}; }
;                     if (q == 0) LSE[((size_t)g * SEQ + cb * 128 + i) * 16 + hh] = lse_own;
	v_mul_f32_e32 v76, v176, v100
	v_mul_f32_e32 v77, v176, v101
	v_cvt_pk_bf16_f32 v76, v76, v77
	v_mul_f32_e32 v77, v176, v102
	v_mul_f32_e32 v78, v176, v103
	v_cvt_pk_bf16_f32 v77, v77, v78
	v_mul_f32_e32 v78, v176, v72
	v_mul_f32_e32 v79, v176, v73
	v_cvt_pk_bf16_f32 v78, v78, v79
	v_mul_f32_e32 v79, v176, v74
	v_mul_f32_e32 v80, v176, v75
	v_cvt_pk_bf16_f32 v79, v79, v80
	v_permlane16_swap_b32_e32 v76, v78
	v_permlane16_swap_b32_e32 v77, v79
	global_store_dwordx4 v[172:173], v[76:79], off offset:-128
	v_mul_f32_e32 v80, v176, v67
	s_nop 0
	v_mul_f32_e32 v76, v176, v68
	v_mul_f32_e32 v77, v176, v69
	v_cvt_pk_bf16_f32 v76, v76, v77
	v_mul_f32_e32 v77, v176, v70
	v_mul_f32_e32 v78, v176, v71
	v_cvt_pk_bf16_f32 v77, v77, v78
	v_mul_f32_e32 v78, v176, v64
	v_mul_f32_e32 v79, v176, v65
	v_cvt_pk_bf16_f32 v78, v78, v79
	v_mul_f32_e32 v79, v176, v66
	v_cvt_pk_bf16_f32 v79, v79, v80
	v_permlane16_swap_b32_e32 v76, v78
	s_nop 0
	v_permlane16_swap_b32_e32 v77, v79
	global_store_dwordx4 v[172:173], v[76:79], off offset:-64
	v_mul_f32_e32 v80, v176, v59
	s_nop 0
	v_mul_f32_e32 v76, v176, v60
	v_mul_f32_e32 v77, v176, v61
	v_cvt_pk_bf16_f32 v76, v76, v77
	v_mul_f32_e32 v77, v176, v62
	v_mul_f32_e32 v78, v176, v63
	v_cvt_pk_bf16_f32 v77, v77, v78
	v_mul_f32_e32 v78, v176, v56
	v_mul_f32_e32 v79, v176, v57
	v_cvt_pk_bf16_f32 v78, v78, v79
	v_mul_f32_e32 v79, v176, v58
	v_cvt_pk_bf16_f32 v79, v79, v80
	v_permlane16_swap_b32_e32 v76, v78
	s_nop 0
	v_permlane16_swap_b32_e32 v77, v79
	global_store_dwordx4 v[172:173], v[76:79], off
	v_mul_f32_e32 v80, v176, v51
	s_nop 0
	v_mul_f32_e32 v76, v176, v52
	v_mul_f32_e32 v77, v176, v53
	v_cvt_pk_bf16_f32 v76, v76, v77
	v_mul_f32_e32 v77, v176, v54
	v_mul_f32_e32 v78, v176, v55
	v_cvt_pk_bf16_f32 v77, v77, v78
	v_mul_f32_e32 v78, v176, v48
	v_mul_f32_e32 v79, v176, v49
	v_cvt_pk_bf16_f32 v78, v78, v79
	v_mul_f32_e32 v79, v176, v50
	v_cvt_pk_bf16_f32 v79, v79, v80
	v_permlane16_swap_b32_e32 v76, v78
	s_nop 0
	v_permlane16_swap_b32_e32 v77, v79
	global_store_dwordx4 v[172:173], v[76:79], off offset:64
	s_and_saveexec_b64 s[58:59], s[38:39]
	s_cbranch_execz .LBB0_334
	s_add_i32 s5, s88, s4
	s_add_i32 s60, s5, 0xffffff80
	v_lshl_add_u64 v[76:77], v[132:133], 0, s[60:61]
	v_lshlrev_b64 v[76:77], 6, v[76:77]
	v_lshl_add_u64 v[76:77], s[28:29], 0, v[76:77]
	global_store_dword v[76:77], v127, off
